# GU and down gemm loops: redundant back-to-back s_setprio 0/1 pairs inside the MFMA blocks deleted (4 per iteration each), on top of v39
# baseline (speedup 1.0000x reference)
; #define PG8_STAGE(bufoff, gbase, voff) do { _Pragma("unroll") for (int _i = 0; _i < 2; ++_i) \
;         __builtin_amdgcn_global_load_lds((const unsigned*)((const char*)(gbase) + (voff)[_i]), (LAS unsigned*)(lds + (bufoff) + ldsw + _i * 8192), 16, 0, 0); } while (0)
; #define PG8_LDA(dst, b, h) do { _Pragma("unroll") for (int m = 0; m < 4; ++m) _Pragma("unroll") for (int k = 0; k < 2; ++k) dst[m][k] = *(const LAS bf16x8*)(lds + PG8_SA(b, h) + aoff + m * 2048 + k * 1024); } while (0)
; #define PG8_LDB(dst, b, h) do { _Pragma("unroll") for (int n = 0; n < 2; ++n) _Pragma("unroll") for (int k = 0; k < 2; ++k) dst[n][k] = *(const LAS bf16x8*)(lds + PG8_SB(b, h) + boff + n * 2048 + k * 1024); } while (0)
; #define PG8_MMA(ai, bj, At, Bt) do { __builtin_amdgcn_s_setprio(1); _Pragma("unroll") for (int m = 0; m < 4; ++m) _Pragma("unroll") for (int n = 0; n < 2; ++n) _Pragma("unroll") for (int k = 0; k < 2; ++k) \
;         acc[ai][bj][m][n] = __builtin_amdgcn_mfma_f32_16x16x32_bf16(Bt[n][k], At[m][k], acc[ai][bj][m][n], 0, 0, 0); __builtin_amdgcn_s_setprio(0); } while (0)
; #define PG8_WAIT_V(n) asm volatile("s_waitcnt vmcnt(" #n ")" ::: "memory")
; #define PG8_WAIT_L(n) asm volatile("s_waitcnt lgkmcnt(" #n ")" ::: "memory")
; #define PG8_BAR __builtin_amdgcn_s_barrier()
; #define PG8_SCHED __builtin_amdgcn_sched_barrier(0)
; template <class Epi, class Addr>
; __device__ __forceinline__ void gemm_phase(LAS unsigned char* lds, const Gemm g, const StaticOrder& S, const Addr& AD, const Epi& E) {
;     ...
;             PG8_LDB(B0, 0, 0); PG8_LDB(B1, 0, 1); PG8_SCHED; PG8_LDA(At, 0, 0); PG8_STAGE(PG8_SA(1, 1), a1 + hstepA, voffA);
;             PG8_WAIT_V(8); PG8_WAIT_L(0); PG8_BAR; PG8_MMA(0, 0, At, B0); PG8_MMA(0, 1, At, B1); PG8_BAR; PG8_SCHED;
;             PG8_LDA(At, 0, 1); PG8_STAGE(PG8_SB(0, 0), b2, voffB); PG8_STAGE(PG8_SB(0, 1), b2 + hstepB, voffB); PG8_STAGE(PG8_SA(0, 0), a2, voffA);
;             PG8_WAIT_V(8); PG8_WAIT_L(0); PG8_BAR; PG8_MMA(1, 0, At, B0); PG8_MMA(1, 1, At, B1); PG8_BAR; PG8_SCHED;
.LBB0_1256:
	s_add_i32 s76, s64, 2
	s_add_u32 s24, s62, 0xfffc0080
	s_addc_u32 s25, s63, -1
	s_add_i32 s28, 0, 0x10000
	s_cmp_eq_u32 s70, s64
	s_cselect_b32 s67, s55, s25
	s_cselect_b32 s66, s57, s24
	s_cselect_b32 s65, s72, s75
	s_cselect_b32 s64, s73, s74
	s_add_i32 s24, 0, 0x14000
	ds_read_b128 v[128:131], v178
	ds_read_b128 v[132:135], v178 offset:1024
	ds_read_b128 v[136:139], v178 offset:2048
	ds_read_b128 v[140:143], v178 offset:3072
	ds_read_b128 v[144:147], v178 offset:16384
	ds_read_b128 v[148:151], v178 offset:17408
	ds_read_b128 v[162:165], v178 offset:18432
	ds_read_b128 v[166:169], v178 offset:19456
	s_add_i32 m0, s17, 0xc000
	ds_read_b128 v[170:173], v187
	ds_read_b128 v[174:177], v187 offset:1024
	ds_read_b128 v[188:191], v187 offset:2048
	ds_read_b128 v[192:195], v187 offset:3072
	ds_read_b128 v[196:199], v187 offset:4096
	ds_read_b128 v[222:225], v187 offset:5120
	ds_read_b128 v[226:229], v187 offset:6144
	ds_read_b128 v[230:233], v187 offset:7168
	global_load_lds_dwordx4 v158, s[62:63]
	s_add_i32 m0, s17, 0xe000
	s_nop 0
	global_load_lds_dwordx4 v160, s[62:63]
	s_waitcnt vmcnt(8)
	s_waitcnt lgkmcnt(0)
	s_barrier
	s_setprio 1
	s_waitcnt lgkmcnt(0)
	v_mfma_f32_16x16x32_bf16 v[124:127], v[128:131], v[170:173], v[124:127]
	v_mfma_f32_16x16x32_bf16 v[116:119], v[136:139], v[170:173], v[116:119]
	v_mfma_f32_16x16x32_bf16 v[108:111], v[128:131], v[188:191], v[108:111]
	v_mfma_f32_16x16x32_bf16 v[100:103], v[136:139], v[188:191], v[100:103]
	v_mfma_f32_16x16x32_bf16 v[92:95], v[128:131], v[196:199], v[92:95]
	v_mfma_f32_16x16x32_bf16 v[84:87], v[136:139], v[196:199], v[84:87]
	v_mfma_f32_16x16x32_bf16 v[76:79], v[128:131], v[226:229], v[76:79]
	v_mfma_f32_16x16x32_bf16 v[68:71], v[136:139], v[226:229], v[68:71]
	v_mfma_f32_16x16x32_bf16 v[124:127], v[132:135], v[174:177], v[124:127]
	v_mfma_f32_16x16x32_bf16 v[116:119], v[140:143], v[174:177], v[116:119]
	v_mfma_f32_16x16x32_bf16 v[108:111], v[132:135], v[192:195], v[108:111]
	v_mfma_f32_16x16x32_bf16 v[100:103], v[140:143], v[192:195], v[100:103]
	v_mfma_f32_16x16x32_bf16 v[92:95], v[132:135], v[222:225], v[92:95]
	v_mfma_f32_16x16x32_bf16 v[84:87], v[140:143], v[222:225], v[84:87]
	v_mfma_f32_16x16x32_bf16 v[76:79], v[132:135], v[230:233], v[76:79]
	v_mfma_f32_16x16x32_bf16 v[68:71], v[140:143], v[230:233], v[68:71]
	v_mfma_f32_16x16x32_bf16 v[120:123], v[144:147], v[170:173], v[120:123]
	v_mfma_f32_16x16x32_bf16 v[112:115], v[162:165], v[170:173], v[112:115]
	v_mfma_f32_16x16x32_bf16 v[104:107], v[144:147], v[188:191], v[104:107]
	v_mfma_f32_16x16x32_bf16 v[96:99], v[162:165], v[188:191], v[96:99]
	v_mfma_f32_16x16x32_bf16 v[88:91], v[144:147], v[196:199], v[88:91]
	v_mfma_f32_16x16x32_bf16 v[80:83], v[162:165], v[196:199], v[80:83]
	v_mfma_f32_16x16x32_bf16 v[72:75], v[144:147], v[226:229], v[72:75]
	v_mfma_f32_16x16x32_bf16 v[64:67], v[162:165], v[226:229], v[64:67]
	v_mfma_f32_16x16x32_bf16 v[120:123], v[148:151], v[174:177], v[120:123]
	v_mfma_f32_16x16x32_bf16 v[112:115], v[166:169], v[174:177], v[112:115]
	v_mfma_f32_16x16x32_bf16 v[104:107], v[148:151], v[192:195], v[104:107]
	v_mfma_f32_16x16x32_bf16 v[96:99], v[166:169], v[192:195], v[96:99]
	v_mfma_f32_16x16x32_bf16 v[88:91], v[148:151], v[222:225], v[88:91]
	v_mfma_f32_16x16x32_bf16 v[80:83], v[166:169], v[222:225], v[80:83]
	v_mfma_f32_16x16x32_bf16 v[72:75], v[148:151], v[230:233], v[72:75]
	v_mfma_f32_16x16x32_bf16 v[64:67], v[166:169], v[230:233], v[64:67]
	s_setprio 0
	s_barrier
	s_add_i32 s25, s28, s15
	s_mov_b32 m0, s25
	ds_read_b128 v[170:173], v187 offset:16384
	ds_read_b128 v[174:177], v187 offset:17408
	ds_read_b128 v[188:191], v187 offset:18432
	ds_read_b128 v[192:195], v187 offset:19456
	ds_read_b128 v[196:199], v187 offset:20480
	ds_read_b128 v[222:225], v187 offset:21504
	ds_read_b128 v[226:229], v187 offset:22528
	ds_read_b128 v[230:233], v187 offset:23552
	global_load_lds_dwordx4 v200, s[64:65]
	s_add_i32 m0, s25, 0x2000
	s_add_u32 s78, s64, 0x40000
	s_addc_u32 s79, s65, 0
	s_add_i32 s24, s24, s15
	global_load_lds_dwordx4 v152, s[64:65]
	s_mov_b32 m0, s24
	s_nop 0
	global_load_lds_dwordx4 v200, s[78:79]
	s_add_i32 m0, s24, 0x2000
	s_nop 0
	global_load_lds_dwordx4 v152, s[78:79]
	s_mov_b32 m0, s17
	s_nop 0
	global_load_lds_dwordx4 v156, s[66:67]
	s_mov_b32 m0, s18
	s_nop 0
	global_load_lds_dwordx4 v154, s[66:67]
	s_waitcnt vmcnt(8)
	s_waitcnt lgkmcnt(0)
	s_barrier
	s_setprio 1
	s_waitcnt lgkmcnt(0)
	v_mfma_f32_16x16x32_bf16 v[60:63], v[128:131], v[170:173], v[60:63]
	v_mfma_f32_16x16x32_bf16 v[52:55], v[136:139], v[170:173], v[52:55]
	v_mfma_f32_16x16x32_bf16 v[44:47], v[128:131], v[188:191], v[44:47]
	v_mfma_f32_16x16x32_bf16 v[36:39], v[136:139], v[188:191], v[36:39]
	v_mfma_f32_16x16x32_bf16 v[28:31], v[128:131], v[196:199], v[28:31]
	v_mfma_f32_16x16x32_bf16 v[20:23], v[136:139], v[196:199], v[20:23]
	v_mfma_f32_16x16x32_bf16 v[12:15], v[128:131], v[226:229], v[12:15]
	v_mfma_f32_16x16x32_bf16 v[4:7], v[136:139], v[226:229], v[4:7]
	v_mfma_f32_16x16x32_bf16 v[60:63], v[132:135], v[174:177], v[60:63]
	v_mfma_f32_16x16x32_bf16 v[52:55], v[140:143], v[174:177], v[52:55]
	v_mfma_f32_16x16x32_bf16 v[44:47], v[132:135], v[192:195], v[44:47]
	v_mfma_f32_16x16x32_bf16 v[36:39], v[140:143], v[192:195], v[36:39]
	v_mfma_f32_16x16x32_bf16 v[28:31], v[132:135], v[222:225], v[28:31]
	v_mfma_f32_16x16x32_bf16 v[20:23], v[140:143], v[222:225], v[20:23]
	v_mfma_f32_16x16x32_bf16 v[12:15], v[132:135], v[230:233], v[12:15]
	v_mfma_f32_16x16x32_bf16 v[4:7], v[140:143], v[230:233], v[4:7]
	v_mfma_f32_16x16x32_bf16 v[56:59], v[144:147], v[170:173], v[56:59]
	v_mfma_f32_16x16x32_bf16 v[48:51], v[162:165], v[170:173], v[48:51]
	v_mfma_f32_16x16x32_bf16 v[40:43], v[144:147], v[188:191], v[40:43]
	v_mfma_f32_16x16x32_bf16 v[32:35], v[162:165], v[188:191], v[32:35]
	v_mfma_f32_16x16x32_bf16 v[24:27], v[144:147], v[196:199], v[24:27]
	v_mfma_f32_16x16x32_bf16 v[16:19], v[162:165], v[196:199], v[16:19]
	v_mfma_f32_16x16x32_bf16 v[8:11], v[144:147], v[226:229], v[8:11]
	v_mfma_f32_16x16x32_bf16 v[0:3], v[162:165], v[226:229], v[0:3]
	v_mfma_f32_16x16x32_bf16 v[56:59], v[148:151], v[174:177], v[56:59]
	v_mfma_f32_16x16x32_bf16 v[48:51], v[166:169], v[174:177], v[48:51]
	v_mfma_f32_16x16x32_bf16 v[40:43], v[148:151], v[192:195], v[40:43]
	v_mfma_f32_16x16x32_bf16 v[32:35], v[166:169], v[192:195], v[32:35]
	v_mfma_f32_16x16x32_bf16 v[24:27], v[148:151], v[222:225], v[24:27]
	v_mfma_f32_16x16x32_bf16 v[16:19], v[166:169], v[222:225], v[16:19]
	v_mfma_f32_16x16x32_bf16 v[8:11], v[148:151], v[230:233], v[8:11]
	v_mfma_f32_16x16x32_bf16 v[0:3], v[166:169], v[230:233], v[0:3]
	s_setprio 0
	s_barrier
; #define PG8_STAGE(bufoff, gbase, voff) do { _Pragma("unroll") for (int _i = 0; _i < 2; ++_i) \
;         __builtin_amdgcn_global_load_lds((const unsigned*)((const char*)(gbase) + (voff)[_i]), (LAS unsigned*)(lds + (bufoff) + ldsw + _i * 8192), 16, 0, 0); } while (0)
; #define PG8_LDA(dst, b, h) do { _Pragma("unroll") for (int m = 0; m < 4; ++m) _Pragma("unroll") for (int k = 0; k < 2; ++k) dst[m][k] = *(const LAS bf16x8*)(lds + PG8_SA(b, h) + aoff + m * 2048 + k * 1024); } while (0)
; #define PG8_LDB(dst, b, h) do { _Pragma("unroll") for (int n = 0; n < 2; ++n) _Pragma("unroll") for (int k = 0; k < 2; ++k) dst[n][k] = *(const LAS bf16x8*)(lds + PG8_SB(b, h) + boff + n * 2048 + k * 1024); } while (0)
; #define PG8_MMA(ai, bj, At, Bt) do { __builtin_amdgcn_s_setprio(1); _Pragma("unroll") for (int m = 0; m < 4; ++m) _Pragma("unroll") for (int n = 0; n < 2; ++n) _Pragma("unroll") for (int k = 0; k < 2; ++k) \
;         acc[ai][bj][m][n] = __builtin_amdgcn_mfma_f32_16x16x32_bf16(Bt[n][k], At[m][k], acc[ai][bj][m][n], 0, 0, 0); __builtin_amdgcn_s_setprio(0); } while (0)
; #define PG8_WAIT_V(n) asm volatile("s_waitcnt vmcnt(" #n ")" ::: "memory")
; #define PG8_WAIT_L(n) asm volatile("s_waitcnt lgkmcnt(" #n ")" ::: "memory")
; #define PG8_BAR __builtin_amdgcn_s_barrier()
; #define PG8_SCHED __builtin_amdgcn_sched_barrier(0)
; template <class Epi, class Addr>
; __device__ __forceinline__ void gemm_phase(LAS unsigned char* lds, const Gemm g, const StaticOrder& S, const Addr& AD, const Epi& E) {
;     ...
;             PG8_LDB(B0, 1, 0); PG8_LDB(B1, 1, 1); PG8_SCHED; PG8_LDA(At, 1, 0); PG8_STAGE(PG8_SA(0, 1), a2 + hstepA, voffA);
;             PG8_WAIT_V(8); PG8_WAIT_L(0); PG8_BAR; PG8_MMA(0, 0, At, B0); PG8_MMA(0, 1, At, B1); PG8_BAR; PG8_SCHED;
;             PG8_LDA(At, 1, 1); PG8_STAGE(PG8_SB(1, 0), b3, voffB); PG8_STAGE(PG8_SB(1, 1), b3 + hstepB, voffB); PG8_STAGE(PG8_SA(1, 0), a3, voffA);
;             PG8_WAIT_V(8); PG8_WAIT_L(0); PG8_BAR; PG8_MMA(1, 0, At, B0); PG8_MMA(1, 1, At, B1); PG8_BAR; PG8_SCHED;
;         }
	s_add_i32 s24, 0, 0x18000
	s_add_i32 s25, 0, 0x1c000
	ds_read_b128 v[128:131], v179
	ds_read_b128 v[132:135], v179 offset:1024
	ds_read_b128 v[136:139], v179 offset:2048
	ds_read_b128 v[140:143], v179 offset:3072
	ds_read_b128 v[144:147], v179 offset:16384
	ds_read_b128 v[148:151], v179 offset:17408
	ds_read_b128 v[162:165], v179 offset:18432
	ds_read_b128 v[166:169], v179 offset:19456
	s_add_u32 s66, s66, 0x40000
	s_addc_u32 s67, s67, 0
	s_mov_b32 m0, s19
	ds_read_b128 v[170:173], v187 offset:32768
	ds_read_b128 v[174:177], v187 offset:33792
	ds_read_b128 v[188:191], v187 offset:34816
	ds_read_b128 v[192:195], v187 offset:35840
	ds_read_b128 v[196:199], v187 offset:36864
	ds_read_b128 v[222:225], v187 offset:37888
	ds_read_b128 v[226:229], v187 offset:38912
	ds_read_b128 v[230:233], v187 offset:39936
	global_load_lds_dwordx4 v156, s[66:67]
	s_mov_b32 m0, s20
	s_nop 0
	global_load_lds_dwordx4 v154, s[66:67]
	s_waitcnt vmcnt(8)
	s_waitcnt lgkmcnt(0)
	s_barrier
	s_setprio 1
	s_waitcnt lgkmcnt(0)
	v_mfma_f32_16x16x32_bf16 v[124:127], v[128:131], v[170:173], v[124:127]
	v_mfma_f32_16x16x32_bf16 v[116:119], v[136:139], v[170:173], v[116:119]
	v_mfma_f32_16x16x32_bf16 v[108:111], v[128:131], v[188:191], v[108:111]
	v_mfma_f32_16x16x32_bf16 v[100:103], v[136:139], v[188:191], v[100:103]
	v_mfma_f32_16x16x32_bf16 v[92:95], v[128:131], v[196:199], v[92:95]
	v_mfma_f32_16x16x32_bf16 v[84:87], v[136:139], v[196:199], v[84:87]
	v_mfma_f32_16x16x32_bf16 v[76:79], v[128:131], v[226:229], v[76:79]
	v_mfma_f32_16x16x32_bf16 v[68:71], v[136:139], v[226:229], v[68:71]
	v_mfma_f32_16x16x32_bf16 v[124:127], v[132:135], v[174:177], v[124:127]
	v_mfma_f32_16x16x32_bf16 v[116:119], v[140:143], v[174:177], v[116:119]
	v_mfma_f32_16x16x32_bf16 v[108:111], v[132:135], v[192:195], v[108:111]
	v_mfma_f32_16x16x32_bf16 v[100:103], v[140:143], v[192:195], v[100:103]
	v_mfma_f32_16x16x32_bf16 v[92:95], v[132:135], v[222:225], v[92:95]
	v_mfma_f32_16x16x32_bf16 v[84:87], v[140:143], v[222:225], v[84:87]
	v_mfma_f32_16x16x32_bf16 v[76:79], v[132:135], v[230:233], v[76:79]
	v_mfma_f32_16x16x32_bf16 v[68:71], v[140:143], v[230:233], v[68:71]
	v_mfma_f32_16x16x32_bf16 v[120:123], v[144:147], v[170:173], v[120:123]
	v_mfma_f32_16x16x32_bf16 v[112:115], v[162:165], v[170:173], v[112:115]
	v_mfma_f32_16x16x32_bf16 v[104:107], v[144:147], v[188:191], v[104:107]
	v_mfma_f32_16x16x32_bf16 v[96:99], v[162:165], v[188:191], v[96:99]
	v_mfma_f32_16x16x32_bf16 v[88:91], v[144:147], v[196:199], v[88:91]
	v_mfma_f32_16x16x32_bf16 v[80:83], v[162:165], v[196:199], v[80:83]
	v_mfma_f32_16x16x32_bf16 v[72:75], v[144:147], v[226:229], v[72:75]
	v_mfma_f32_16x16x32_bf16 v[64:67], v[162:165], v[226:229], v[64:67]
	v_mfma_f32_16x16x32_bf16 v[120:123], v[148:151], v[174:177], v[120:123]
	v_mfma_f32_16x16x32_bf16 v[112:115], v[166:169], v[174:177], v[112:115]
	v_mfma_f32_16x16x32_bf16 v[104:107], v[148:151], v[192:195], v[104:107]
	v_mfma_f32_16x16x32_bf16 v[96:99], v[166:169], v[192:195], v[96:99]
	v_mfma_f32_16x16x32_bf16 v[88:91], v[148:151], v[222:225], v[88:91]
	v_mfma_f32_16x16x32_bf16 v[80:83], v[166:169], v[222:225], v[80:83]
	v_mfma_f32_16x16x32_bf16 v[72:75], v[148:151], v[230:233], v[72:75]
	v_mfma_f32_16x16x32_bf16 v[64:67], v[166:169], v[230:233], v[64:67]
	s_setprio 0
	s_barrier
	s_add_i32 s24, s24, s15
	s_add_u32 s78, s64, s42
	s_addc_u32 s79, s65, s43
	s_mov_b32 m0, s24
	ds_read_b128 v[170:173], v187 offset:49152
	ds_read_b128 v[174:177], v187 offset:50176
	ds_read_b128 v[188:191], v187 offset:51200
	ds_read_b128 v[192:195], v187 offset:52224
	ds_read_b128 v[196:199], v187 offset:53248
	ds_read_b128 v[222:225], v187 offset:54272
	ds_read_b128 v[226:229], v187 offset:55296
	ds_read_b128 v[230:233], v187 offset:56320
	global_load_lds_dwordx4 v200, s[78:79]
	s_add_i32 m0, s24, 0x2000
	s_add_u32 s64, s64, 0x40080
	s_addc_u32 s65, s65, 0
	s_add_i32 s24, s25, s15
	global_load_lds_dwordx4 v152, s[78:79]
	s_mov_b32 m0, s24
	s_add_u32 s78, s66, s42
	s_addc_u32 s79, s67, s43
	global_load_lds_dwordx4 v200, s[64:65]
	s_add_i32 m0, s24, 0x2000
	s_sub_u32 s78, s78, 0x40000
	s_subb_u32 s79, s79, 0
	global_load_lds_dwordx4 v152, s[64:65]
	s_mov_b32 m0, s68
	s_nop 0
	global_load_lds_dwordx4 v156, s[78:79]
	s_mov_b32 m0, s69
	s_nop 0
	global_load_lds_dwordx4 v154, s[78:79]
	s_waitcnt vmcnt(8)
	s_waitcnt lgkmcnt(0)
	s_barrier
	s_setprio 1
	s_waitcnt lgkmcnt(0)
	v_mfma_f32_16x16x32_bf16 v[60:63], v[128:131], v[170:173], v[60:63]
	v_mfma_f32_16x16x32_bf16 v[52:55], v[136:139], v[170:173], v[52:55]
	v_mfma_f32_16x16x32_bf16 v[44:47], v[128:131], v[188:191], v[44:47]
	v_mfma_f32_16x16x32_bf16 v[36:39], v[136:139], v[188:191], v[36:39]
	v_mfma_f32_16x16x32_bf16 v[28:31], v[128:131], v[196:199], v[28:31]
	v_mfma_f32_16x16x32_bf16 v[20:23], v[136:139], v[196:199], v[20:23]
	v_mfma_f32_16x16x32_bf16 v[12:15], v[128:131], v[226:229], v[12:15]
	v_mfma_f32_16x16x32_bf16 v[4:7], v[136:139], v[226:229], v[4:7]
	v_mfma_f32_16x16x32_bf16 v[60:63], v[132:135], v[174:177], v[60:63]
	v_mfma_f32_16x16x32_bf16 v[52:55], v[140:143], v[174:177], v[52:55]
	v_mfma_f32_16x16x32_bf16 v[44:47], v[132:135], v[192:195], v[44:47]
	v_mfma_f32_16x16x32_bf16 v[36:39], v[140:143], v[192:195], v[36:39]
	v_mfma_f32_16x16x32_bf16 v[28:31], v[132:135], v[222:225], v[28:31]
	v_mfma_f32_16x16x32_bf16 v[20:23], v[140:143], v[222:225], v[20:23]
	v_mfma_f32_16x16x32_bf16 v[12:15], v[132:135], v[230:233], v[12:15]
	v_mfma_f32_16x16x32_bf16 v[4:7], v[140:143], v[230:233], v[4:7]
	v_mfma_f32_16x16x32_bf16 v[56:59], v[144:147], v[170:173], v[56:59]
	v_mfma_f32_16x16x32_bf16 v[48:51], v[162:165], v[170:173], v[48:51]
	v_mfma_f32_16x16x32_bf16 v[40:43], v[144:147], v[188:191], v[40:43]
	v_mfma_f32_16x16x32_bf16 v[32:35], v[162:165], v[188:191], v[32:35]
	v_mfma_f32_16x16x32_bf16 v[24:27], v[144:147], v[196:199], v[24:27]
	v_mfma_f32_16x16x32_bf16 v[16:19], v[162:165], v[196:199], v[16:19]
	v_mfma_f32_16x16x32_bf16 v[8:11], v[144:147], v[226:229], v[8:11]
	v_mfma_f32_16x16x32_bf16 v[0:3], v[162:165], v[226:229], v[0:3]
	v_mfma_f32_16x16x32_bf16 v[56:59], v[148:151], v[174:177], v[56:59]
	v_mfma_f32_16x16x32_bf16 v[48:51], v[166:169], v[174:177], v[48:51]
	v_mfma_f32_16x16x32_bf16 v[40:43], v[148:151], v[192:195], v[40:43]
	v_mfma_f32_16x16x32_bf16 v[32:35], v[166:169], v[192:195], v[32:35]
	v_mfma_f32_16x16x32_bf16 v[24:27], v[148:151], v[222:225], v[24:27]
	v_mfma_f32_16x16x32_bf16 v[16:19], v[166:169], v[222:225], v[16:19]
	v_mfma_f32_16x16x32_bf16 v[8:11], v[148:151], v[230:233], v[8:11]
	v_mfma_f32_16x16x32_bf16 v[0:3], v[166:169], v[230:233], v[0:3]
	s_setprio 0
	s_barrier
	s_add_u32 s62, s62, 0x100
	s_addc_u32 s63, s63, 0
	s_add_u32 s74, s74, 0x100
	s_addc_u32 s75, s75, 0
	s_cmp_ge_i32 s76, s21
	s_mov_b32 s64, s76
	s_cbranch_scc0 .LBB0_1256

; #define PG8_STAGE(bufoff, gbase, voff) do { _Pragma("unroll") for (int _i = 0; _i < 2; ++_i) \
;         __builtin_amdgcn_global_load_lds((const unsigned*)((const char*)(gbase) + (voff)[_i]), (LAS unsigned*)(lds + (bufoff) + ldsw + _i * 8192), 16, 0, 0); } while (0)
; #define PG8_LDA(dst, b, h) do { _Pragma("unroll") for (int m = 0; m < 4; ++m) _Pragma("unroll") for (int k = 0; k < 2; ++k) dst[m][k] = *(const LAS bf16x8*)(lds + PG8_SA(b, h) + aoff + m * 2048 + k * 1024); } while (0)
; #define PG8_LDB(dst, b, h) do { _Pragma("unroll") for (int n = 0; n < 2; ++n) _Pragma("unroll") for (int k = 0; k < 2; ++k) dst[n][k] = *(const LAS bf16x8*)(lds + PG8_SB(b, h) + boff + n * 2048 + k * 1024); } while (0)
; #define PG8_MMA(ai, bj, At, Bt) do { __builtin_amdgcn_s_setprio(1); _Pragma("unroll") for (int m = 0; m < 4; ++m) _Pragma("unroll") for (int n = 0; n < 2; ++n) _Pragma("unroll") for (int k = 0; k < 2; ++k) \
;         acc[ai][bj][m][n] = __builtin_amdgcn_mfma_f32_16x16x32_bf16(Bt[n][k], At[m][k], acc[ai][bj][m][n], 0, 0, 0); __builtin_amdgcn_s_setprio(0); } while (0)
; #define PG8_WAIT_V(n) asm volatile("s_waitcnt vmcnt(" #n ")" ::: "memory")
; #define PG8_WAIT_L(n) asm volatile("s_waitcnt lgkmcnt(" #n ")" ::: "memory")
; #define PG8_BAR __builtin_amdgcn_s_barrier()
; #define PG8_SCHED __builtin_amdgcn_sched_barrier(0)
; template <class Epi, class Addr>
; __device__ __forceinline__ void gemm_phase(LAS unsigned char* lds, const Gemm g, const StaticOrder& S, const Addr& AD, const Epi& E) {
;     ...
;             PG8_LDB(B0, 0, 0); PG8_LDB(B1, 0, 1); PG8_SCHED; PG8_LDA(At, 0, 0); PG8_STAGE(PG8_SA(1, 1), a1 + hstepA, voffA);
;             PG8_WAIT_V(8); PG8_WAIT_L(0); PG8_BAR; PG8_MMA(0, 0, At, B0); PG8_MMA(0, 1, At, B1); PG8_BAR; PG8_SCHED;
;             PG8_LDA(At, 0, 1); PG8_STAGE(PG8_SB(0, 0), b2, voffB); PG8_STAGE(PG8_SB(0, 1), b2 + hstepB, voffB); PG8_STAGE(PG8_SA(0, 0), a2, voffA);
;             PG8_WAIT_V(8); PG8_WAIT_L(0); PG8_BAR; PG8_MMA(1, 0, At, B0); PG8_MMA(1, 1, At, B1); PG8_BAR; PG8_SCHED;
.LBB0_1332:
	s_add_i32 s81, s66, 2
	s_add_u32 s6, s8, 0x100
	s_addc_u32 s7, s9, 0
	s_add_i32 s24, 0, 0x10000
	s_cmp_eq_u32 s74, s66
	s_cselect_b32 s69, s63, s7
	s_cselect_b32 s68, s62, s6
	s_cselect_b32 s67, s65, s80
	s_cselect_b32 s66, s64, s79
	s_add_i32 s25, 0, 0x14000
	ds_read_b128 v[134:137], v198
	ds_read_b128 v[138:141], v198 offset:1024
	ds_read_b128 v[142:145], v198 offset:2048
	ds_read_b128 v[146:149], v198 offset:3072
	ds_read_b128 v[150:153], v198 offset:16384
	ds_read_b128 v[154:157], v198 offset:17408
	ds_read_b128 v[158:161], v198 offset:18432
	ds_read_b128 v[162:165], v198 offset:19456
	s_add_i32 m0, s17, 0xc000
	ds_read_b128 v[166:169], v243
	ds_read_b128 v[170:173], v243 offset:1024
	ds_read_b128 v[174:177], v243 offset:2048
	ds_read_b128 v[178:181], v243 offset:3072
	ds_read_b128 v[182:185], v243 offset:4096
	ds_read_b128 v[186:189], v243 offset:5120
	ds_read_b128 v[190:193], v243 offset:6144
	ds_read_b128 v[194:197], v243 offset:7168
	global_load_lds_dwordx4 v130, s[8:9]
	s_add_i32 m0, s17, 0xe000
	s_nop 0
	global_load_lds_dwordx4 v132, s[8:9]
	s_waitcnt vmcnt(8)
	s_waitcnt lgkmcnt(0)
	s_barrier
	s_setprio 1
	s_waitcnt lgkmcnt(0)
	v_mfma_f32_16x16x32_bf16 v[124:127], v[134:137], v[166:169], v[124:127]
	v_mfma_f32_16x16x32_bf16 v[120:123], v[142:145], v[166:169], v[120:123]
	v_mfma_f32_16x16x32_bf16 v[116:119], v[134:137], v[174:177], v[116:119]
	v_mfma_f32_16x16x32_bf16 v[112:115], v[142:145], v[174:177], v[112:115]
	v_mfma_f32_16x16x32_bf16 v[104:107], v[134:137], v[182:185], v[104:107]
	v_mfma_f32_16x16x32_bf16 v[96:99], v[142:145], v[182:185], v[96:99]
	v_mfma_f32_16x16x32_bf16 v[88:91], v[134:137], v[190:193], v[88:91]
	v_mfma_f32_16x16x32_bf16 v[80:83], v[142:145], v[190:193], v[80:83]
	v_mfma_f32_16x16x32_bf16 v[124:127], v[138:141], v[170:173], v[124:127]
	v_mfma_f32_16x16x32_bf16 v[120:123], v[146:149], v[170:173], v[120:123]
	v_mfma_f32_16x16x32_bf16 v[116:119], v[138:141], v[178:181], v[116:119]
	v_mfma_f32_16x16x32_bf16 v[112:115], v[146:149], v[178:181], v[112:115]
	v_mfma_f32_16x16x32_bf16 v[104:107], v[138:141], v[186:189], v[104:107]
	v_mfma_f32_16x16x32_bf16 v[96:99], v[146:149], v[186:189], v[96:99]
	v_mfma_f32_16x16x32_bf16 v[88:91], v[138:141], v[194:197], v[88:91]
	v_mfma_f32_16x16x32_bf16 v[80:83], v[146:149], v[194:197], v[80:83]
	v_mfma_f32_16x16x32_bf16 v[108:111], v[150:153], v[166:169], v[108:111]
	v_mfma_f32_16x16x32_bf16 v[100:103], v[158:161], v[166:169], v[100:103]
	v_mfma_f32_16x16x32_bf16 v[92:95], v[150:153], v[174:177], v[92:95]
	v_mfma_f32_16x16x32_bf16 v[84:87], v[158:161], v[174:177], v[84:87]
	v_mfma_f32_16x16x32_bf16 v[76:79], v[150:153], v[182:185], v[76:79]
	v_mfma_f32_16x16x32_bf16 v[72:75], v[158:161], v[182:185], v[72:75]
	v_mfma_f32_16x16x32_bf16 v[68:71], v[150:153], v[190:193], v[68:71]
	v_mfma_f32_16x16x32_bf16 v[64:67], v[158:161], v[190:193], v[64:67]
	v_mfma_f32_16x16x32_bf16 v[108:111], v[154:157], v[170:173], v[108:111]
	v_mfma_f32_16x16x32_bf16 v[100:103], v[162:165], v[170:173], v[100:103]
	v_mfma_f32_16x16x32_bf16 v[92:95], v[154:157], v[178:181], v[92:95]
	v_mfma_f32_16x16x32_bf16 v[84:87], v[162:165], v[178:181], v[84:87]
	v_mfma_f32_16x16x32_bf16 v[76:79], v[154:157], v[186:189], v[76:79]
	v_mfma_f32_16x16x32_bf16 v[72:75], v[162:165], v[186:189], v[72:75]
	v_mfma_f32_16x16x32_bf16 v[68:71], v[154:157], v[194:197], v[68:71]
	v_mfma_f32_16x16x32_bf16 v[64:67], v[162:165], v[194:197], v[64:67]
	s_setprio 0
	s_barrier
	s_add_i32 s8, s24, s2
	s_mov_b32 m0, s8
	ds_read_b128 v[166:169], v243 offset:16384
	ds_read_b128 v[170:173], v243 offset:17408
	ds_read_b128 v[174:177], v243 offset:18432
	ds_read_b128 v[178:181], v243 offset:19456
	ds_read_b128 v[182:185], v243 offset:20480
	ds_read_b128 v[186:189], v243 offset:21504
	ds_read_b128 v[190:193], v243 offset:22528
	ds_read_b128 v[194:197], v243 offset:23552
	global_load_lds_dwordx4 v200, s[66:67]
	s_add_i32 m0, s8, 0x2000
	s_add_u32 s8, s66, 0xb0000
	s_addc_u32 s9, s67, 0
	s_add_i32 s24, s25, s2
	global_load_lds_dwordx4 v128, s[66:67]
	s_mov_b32 m0, s24
	s_nop 0
	global_load_lds_dwordx4 v200, s[8:9]
	s_add_i32 m0, s24, 0x2000
	s_nop 0
	global_load_lds_dwordx4 v128, s[8:9]
	s_mov_b32 m0, s17
	s_nop 0
	global_load_lds_dwordx4 v200, s[68:69]
	s_mov_b32 m0, s18
	s_nop 0
	global_load_lds_dwordx4 v128, s[68:69]
	s_waitcnt vmcnt(8)
	s_waitcnt lgkmcnt(0)
	s_barrier
	s_setprio 1
	s_waitcnt lgkmcnt(0)
	v_mfma_f32_16x16x32_bf16 v[60:63], v[134:137], v[166:169], v[60:63]
	v_mfma_f32_16x16x32_bf16 v[56:59], v[142:145], v[166:169], v[56:59]
	v_mfma_f32_16x16x32_bf16 v[52:55], v[134:137], v[174:177], v[52:55]
	v_mfma_f32_16x16x32_bf16 v[48:51], v[142:145], v[174:177], v[48:51]
	v_mfma_f32_16x16x32_bf16 v[40:43], v[134:137], v[182:185], v[40:43]
	v_mfma_f32_16x16x32_bf16 v[32:35], v[142:145], v[182:185], v[32:35]
	v_mfma_f32_16x16x32_bf16 v[24:27], v[134:137], v[190:193], v[24:27]
	v_mfma_f32_16x16x32_bf16 v[16:19], v[142:145], v[190:193], v[16:19]
	v_mfma_f32_16x16x32_bf16 v[60:63], v[138:141], v[170:173], v[60:63]
	v_mfma_f32_16x16x32_bf16 v[56:59], v[146:149], v[170:173], v[56:59]
	v_mfma_f32_16x16x32_bf16 v[52:55], v[138:141], v[178:181], v[52:55]
	v_mfma_f32_16x16x32_bf16 v[48:51], v[146:149], v[178:181], v[48:51]
	v_mfma_f32_16x16x32_bf16 v[40:43], v[138:141], v[186:189], v[40:43]
	v_mfma_f32_16x16x32_bf16 v[32:35], v[146:149], v[186:189], v[32:35]
	v_mfma_f32_16x16x32_bf16 v[24:27], v[138:141], v[194:197], v[24:27]
	v_mfma_f32_16x16x32_bf16 v[16:19], v[146:149], v[194:197], v[16:19]
	v_mfma_f32_16x16x32_bf16 v[44:47], v[150:153], v[166:169], v[44:47]
	v_mfma_f32_16x16x32_bf16 v[36:39], v[158:161], v[166:169], v[36:39]
	v_mfma_f32_16x16x32_bf16 v[28:31], v[150:153], v[174:177], v[28:31]
	v_mfma_f32_16x16x32_bf16 v[20:23], v[158:161], v[174:177], v[20:23]
	v_mfma_f32_16x16x32_bf16 v[12:15], v[150:153], v[182:185], v[12:15]
	v_mfma_f32_16x16x32_bf16 v[8:11], v[158:161], v[182:185], v[8:11]
	v_mfma_f32_16x16x32_bf16 v[4:7], v[150:153], v[190:193], v[4:7]
	v_mfma_f32_16x16x32_bf16 v[0:3], v[158:161], v[190:193], v[0:3]
	v_mfma_f32_16x16x32_bf16 v[44:47], v[154:157], v[170:173], v[44:47]
	v_mfma_f32_16x16x32_bf16 v[36:39], v[162:165], v[170:173], v[36:39]
	v_mfma_f32_16x16x32_bf16 v[28:31], v[154:157], v[178:181], v[28:31]
	v_mfma_f32_16x16x32_bf16 v[20:23], v[162:165], v[178:181], v[20:23]
	v_mfma_f32_16x16x32_bf16 v[12:15], v[154:157], v[186:189], v[12:15]
	v_mfma_f32_16x16x32_bf16 v[8:11], v[162:165], v[186:189], v[8:11]
	v_mfma_f32_16x16x32_bf16 v[4:7], v[154:157], v[194:197], v[4:7]
	v_mfma_f32_16x16x32_bf16 v[0:3], v[162:165], v[194:197], v[0:3]
	s_setprio 0
	s_barrier
; #define PG8_STAGE(bufoff, gbase, voff) do { _Pragma("unroll") for (int _i = 0; _i < 2; ++_i) \
;         __builtin_amdgcn_global_load_lds((const unsigned*)((const char*)(gbase) + (voff)[_i]), (LAS unsigned*)(lds + (bufoff) + ldsw + _i * 8192), 16, 0, 0); } while (0)
; #define PG8_LDA(dst, b, h) do { _Pragma("unroll") for (int m = 0; m < 4; ++m) _Pragma("unroll") for (int k = 0; k < 2; ++k) dst[m][k] = *(const LAS bf16x8*)(lds + PG8_SA(b, h) + aoff + m * 2048 + k * 1024); } while (0)
; #define PG8_LDB(dst, b, h) do { _Pragma("unroll") for (int n = 0; n < 2; ++n) _Pragma("unroll") for (int k = 0; k < 2; ++k) dst[n][k] = *(const LAS bf16x8*)(lds + PG8_SB(b, h) + boff + n * 2048 + k * 1024); } while (0)
; #define PG8_MMA(ai, bj, At, Bt) do { __builtin_amdgcn_s_setprio(1); _Pragma("unroll") for (int m = 0; m < 4; ++m) _Pragma("unroll") for (int n = 0; n < 2; ++n) _Pragma("unroll") for (int k = 0; k < 2; ++k) \
;         acc[ai][bj][m][n] = __builtin_amdgcn_mfma_f32_16x16x32_bf16(Bt[n][k], At[m][k], acc[ai][bj][m][n], 0, 0, 0); __builtin_amdgcn_s_setprio(0); } while (0)
; #define PG8_WAIT_V(n) asm volatile("s_waitcnt vmcnt(" #n ")" ::: "memory")
; #define PG8_WAIT_L(n) asm volatile("s_waitcnt lgkmcnt(" #n ")" ::: "memory")
; #define PG8_BAR __builtin_amdgcn_s_barrier()
; #define PG8_SCHED __builtin_amdgcn_sched_barrier(0)
; template <class Epi, class Addr>
; __device__ __forceinline__ void gemm_phase(LAS unsigned char* lds, const Gemm g, const StaticOrder& S, const Addr& AD, const Epi& E) {
;     ...
;             PG8_LDB(B0, 1, 0); PG8_LDB(B1, 1, 1); PG8_SCHED; PG8_LDA(At, 1, 0); PG8_STAGE(PG8_SA(0, 1), a2 + hstepA, voffA);
;             PG8_WAIT_V(8); PG8_WAIT_L(0); PG8_BAR; PG8_MMA(0, 0, At, B0); PG8_MMA(0, 1, At, B1); PG8_BAR; PG8_SCHED;
;             PG8_LDA(At, 1, 1); PG8_STAGE(PG8_SB(1, 0), b3, voffB); PG8_STAGE(PG8_SB(1, 1), b3 + hstepB, voffB); PG8_STAGE(PG8_SA(1, 0), a3, voffA);
;             PG8_WAIT_V(8); PG8_WAIT_L(0); PG8_BAR; PG8_MMA(1, 0, At, B0); PG8_MMA(1, 1, At, B1); PG8_BAR; PG8_SCHED;
	s_add_i32 s24, 0, 0x18000
	s_add_i32 s25, 0, 0x1c000
	ds_read_b128 v[134:137], v199
	ds_read_b128 v[138:141], v199 offset:1024
	ds_read_b128 v[142:145], v199 offset:2048
	ds_read_b128 v[146:149], v199 offset:3072
	ds_read_b128 v[150:153], v199 offset:16384
	ds_read_b128 v[154:157], v199 offset:17408
	ds_read_b128 v[158:161], v199 offset:18432
	ds_read_b128 v[162:165], v199 offset:19456
	s_add_u32 s8, s68, 0xb0000
	s_addc_u32 s9, s69, 0
	s_mov_b32 m0, s19
	ds_read_b128 v[166:169], v243 offset:32768
	ds_read_b128 v[170:173], v243 offset:33792
	ds_read_b128 v[174:177], v243 offset:34816
	ds_read_b128 v[178:181], v243 offset:35840
	ds_read_b128 v[182:185], v243 offset:36864
	ds_read_b128 v[186:189], v243 offset:37888
	ds_read_b128 v[190:193], v243 offset:38912
	ds_read_b128 v[194:197], v243 offset:39936
	global_load_lds_dwordx4 v200, s[8:9]
	s_mov_b32 m0, s20
	s_nop 0
	global_load_lds_dwordx4 v128, s[8:9]
	s_waitcnt vmcnt(8)
	s_waitcnt lgkmcnt(0)
	s_barrier
	s_setprio 1
	s_waitcnt lgkmcnt(0)
	v_mfma_f32_16x16x32_bf16 v[124:127], v[134:137], v[166:169], v[124:127]
	v_mfma_f32_16x16x32_bf16 v[120:123], v[142:145], v[166:169], v[120:123]
	v_mfma_f32_16x16x32_bf16 v[116:119], v[134:137], v[174:177], v[116:119]
	v_mfma_f32_16x16x32_bf16 v[112:115], v[142:145], v[174:177], v[112:115]
	v_mfma_f32_16x16x32_bf16 v[104:107], v[134:137], v[182:185], v[104:107]
	v_mfma_f32_16x16x32_bf16 v[96:99], v[142:145], v[182:185], v[96:99]
	v_mfma_f32_16x16x32_bf16 v[88:91], v[134:137], v[190:193], v[88:91]
	v_mfma_f32_16x16x32_bf16 v[80:83], v[142:145], v[190:193], v[80:83]
	v_mfma_f32_16x16x32_bf16 v[124:127], v[138:141], v[170:173], v[124:127]
	v_mfma_f32_16x16x32_bf16 v[120:123], v[146:149], v[170:173], v[120:123]
	v_mfma_f32_16x16x32_bf16 v[116:119], v[138:141], v[178:181], v[116:119]
	v_mfma_f32_16x16x32_bf16 v[112:115], v[146:149], v[178:181], v[112:115]
	v_mfma_f32_16x16x32_bf16 v[104:107], v[138:141], v[186:189], v[104:107]
	v_mfma_f32_16x16x32_bf16 v[96:99], v[146:149], v[186:189], v[96:99]
	v_mfma_f32_16x16x32_bf16 v[88:91], v[138:141], v[194:197], v[88:91]
	v_mfma_f32_16x16x32_bf16 v[80:83], v[146:149], v[194:197], v[80:83]
	v_mfma_f32_16x16x32_bf16 v[108:111], v[150:153], v[166:169], v[108:111]
	v_mfma_f32_16x16x32_bf16 v[100:103], v[158:161], v[166:169], v[100:103]
	v_mfma_f32_16x16x32_bf16 v[92:95], v[150:153], v[174:177], v[92:95]
	v_mfma_f32_16x16x32_bf16 v[84:87], v[158:161], v[174:177], v[84:87]
	v_mfma_f32_16x16x32_bf16 v[76:79], v[150:153], v[182:185], v[76:79]
	v_mfma_f32_16x16x32_bf16 v[72:75], v[158:161], v[182:185], v[72:75]
	v_mfma_f32_16x16x32_bf16 v[68:71], v[150:153], v[190:193], v[68:71]
	v_mfma_f32_16x16x32_bf16 v[64:67], v[158:161], v[190:193], v[64:67]
	v_mfma_f32_16x16x32_bf16 v[108:111], v[154:157], v[170:173], v[108:111]
	v_mfma_f32_16x16x32_bf16 v[100:103], v[162:165], v[170:173], v[100:103]
	v_mfma_f32_16x16x32_bf16 v[92:95], v[154:157], v[178:181], v[92:95]
	v_mfma_f32_16x16x32_bf16 v[84:87], v[162:165], v[178:181], v[84:87]
	v_mfma_f32_16x16x32_bf16 v[76:79], v[154:157], v[186:189], v[76:79]
	v_mfma_f32_16x16x32_bf16 v[72:75], v[162:165], v[186:189], v[72:75]
	v_mfma_f32_16x16x32_bf16 v[68:71], v[154:157], v[194:197], v[68:71]
	v_mfma_f32_16x16x32_bf16 v[64:67], v[162:165], v[194:197], v[64:67]
	s_setprio 0
	s_barrier
	s_add_i32 s8, s24, s2
	s_mov_b32 m0, s8
	s_add_u32 s8, s66, 0x80
	s_addc_u32 s9, s67, 0
	ds_read_b128 v[166:169], v243 offset:49152
	ds_read_b128 v[170:173], v243 offset:50176
	ds_read_b128 v[174:177], v243 offset:51200
	ds_read_b128 v[178:181], v243 offset:52224
	ds_read_b128 v[182:185], v243 offset:53248
	ds_read_b128 v[186:189], v243 offset:54272
	ds_read_b128 v[190:193], v243 offset:55296
	ds_read_b128 v[194:197], v243 offset:56320
	global_load_lds_dwordx4 v200, s[8:9]
	s_add_i32 m0, m0, 0x2000
	s_add_i32 s24, s25, s2
	s_nop 0
	global_load_lds_dwordx4 v128, s[8:9]
	s_add_u32 s8, s66, 0xb0080
	s_addc_u32 s9, s67, 0
	s_mov_b32 m0, s24
	s_nop 0
	global_load_lds_dwordx4 v200, s[8:9]
	s_add_i32 m0, s24, 0x2000
	s_nop 0
	global_load_lds_dwordx4 v128, s[8:9]
	s_add_u32 s8, s68, 0x80
	s_addc_u32 s9, s69, 0
	s_mov_b32 m0, s72
	s_nop 0
	global_load_lds_dwordx4 v200, s[8:9]
	s_mov_b32 m0, s73
	s_nop 0
	global_load_lds_dwordx4 v128, s[8:9]
	s_waitcnt vmcnt(8)
	s_waitcnt lgkmcnt(0)
	s_barrier
; #define PG8_MMA(ai, bj, At, Bt) do { __builtin_amdgcn_s_setprio(1); _Pragma("unroll") for (int m = 0; m < 4; ++m) _Pragma("unroll") for (int n = 0; n < 2; ++n) _Pragma("unroll") for (int k = 0; k < 2; ++k) \
;         acc[ai][bj][m][n] = __builtin_amdgcn_mfma_f32_16x16x32_bf16(Bt[n][k], At[m][k], acc[ai][bj][m][n], 0, 0, 0); __builtin_amdgcn_s_setprio(0); } while (0)
; #define PG8_WAIT_V(n) asm volatile("s_waitcnt vmcnt(" #n ")" ::: "memory")
; #define PG8_WAIT_L(n) asm volatile("s_waitcnt lgkmcnt(" #n ")" ::: "memory")
; #define PG8_BAR __builtin_amdgcn_s_barrier()
; #define PG8_SCHED __builtin_amdgcn_sched_barrier(0)
;     __device__ __forceinline__ void operator()(Acc& acc, const Unit& u, int wr, int wc, int fr, int fq, LAS unsigned char* xch) const {
;     ...
;             for (int q = 0; q < 4; ++q) v[q] = pre[g % PD][q] + acc[ai][q >> 1][m][q & 1] * alpha;
; template <class Epi, class Addr>
; __device__ __forceinline__ void gemm_phase(LAS unsigned char* lds, const Gemm g, const StaticOrder& S, const Addr& AD, const Epi& E) {
;     ...
;             PG8_WAIT_V(8); PG8_WAIT_L(0); PG8_BAR; PG8_MMA(1, 0, At, B0); PG8_MMA(1, 1, At, B1); PG8_BAR; PG8_SCHED;
;         }
	s_setprio 1
	s_waitcnt lgkmcnt(0)
	v_mfma_f32_16x16x32_bf16 v[60:63], v[134:137], v[166:169], v[60:63]
	v_mfma_f32_16x16x32_bf16 v[56:59], v[142:145], v[166:169], v[56:59]
	v_mfma_f32_16x16x32_bf16 v[52:55], v[134:137], v[174:177], v[52:55]
	v_mfma_f32_16x16x32_bf16 v[48:51], v[142:145], v[174:177], v[48:51]
	v_mfma_f32_16x16x32_bf16 v[40:43], v[134:137], v[182:185], v[40:43]
	v_mfma_f32_16x16x32_bf16 v[32:35], v[142:145], v[182:185], v[32:35]
	v_mfma_f32_16x16x32_bf16 v[24:27], v[134:137], v[190:193], v[24:27]
	v_mfma_f32_16x16x32_bf16 v[16:19], v[142:145], v[190:193], v[16:19]
	v_mfma_f32_16x16x32_bf16 v[60:63], v[138:141], v[170:173], v[60:63]
	v_mfma_f32_16x16x32_bf16 v[56:59], v[146:149], v[170:173], v[56:59]
	v_mfma_f32_16x16x32_bf16 v[52:55], v[138:141], v[178:181], v[52:55]
	v_mfma_f32_16x16x32_bf16 v[48:51], v[146:149], v[178:181], v[48:51]
	v_mfma_f32_16x16x32_bf16 v[40:43], v[138:141], v[186:189], v[40:43]
	v_mfma_f32_16x16x32_bf16 v[32:35], v[146:149], v[186:189], v[32:35]
	v_mfma_f32_16x16x32_bf16 v[24:27], v[138:141], v[194:197], v[24:27]
	v_mfma_f32_16x16x32_bf16 v[16:19], v[146:149], v[194:197], v[16:19]
	v_mfma_f32_16x16x32_bf16 v[44:47], v[150:153], v[166:169], v[44:47]
	v_mfma_f32_16x16x32_bf16 v[36:39], v[158:161], v[166:169], v[36:39]
	v_mfma_f32_16x16x32_bf16 v[28:31], v[150:153], v[174:177], v[28:31]
	v_mfma_f32_16x16x32_bf16 v[20:23], v[158:161], v[174:177], v[20:23]
	v_mfma_f32_16x16x32_bf16 v[12:15], v[150:153], v[182:185], v[12:15]
	v_mfma_f32_16x16x32_bf16 v[8:11], v[158:161], v[182:185], v[8:11]
	v_mfma_f32_16x16x32_bf16 v[4:7], v[150:153], v[190:193], v[4:7]
	v_mfma_f32_16x16x32_bf16 v[0:3], v[158:161], v[190:193], v[0:3]
	v_mfma_f32_16x16x32_bf16 v[44:47], v[154:157], v[170:173], v[44:47]
	v_mfma_f32_16x16x32_bf16 v[36:39], v[162:165], v[170:173], v[36:39]
	v_mfma_f32_16x16x32_bf16 v[28:31], v[154:157], v[178:181], v[28:31]
	v_mfma_f32_16x16x32_bf16 v[20:23], v[162:165], v[178:181], v[20:23]
	v_mfma_f32_16x16x32_bf16 v[12:15], v[154:157], v[186:189], v[12:15]
	v_mfma_f32_16x16x32_bf16 v[8:11], v[162:165], v[186:189], v[8:11]
	v_mfma_f32_16x16x32_bf16 v[4:7], v[154:157], v[194:197], v[4:7]
	v_mfma_f32_16x16x32_bf16 v[0:3], v[162:165], v[194:197], v[0:3]
	s_setprio 0
	s_barrier
	s_add_u32 s79, s79, 0x100
	s_addc_u32 s80, s80, 0
	s_cmp_ge_i32 s81, s23
	s_mov_b64 s[8:9], s[6:7]
	s_mov_b32 s66, s81
	s_cbranch_scc0 .LBB0_1332
	v_pk_mul_f32 v[188:189], v[126:127], 0.5 op_sel_hi:[1,0]
	v_pk_mul_f32 v[226:227], v[124:125], 0.5 op_sel_hi:[1,0]
	v_pk_mul_f32 v[196:197], v[122:123], 0.5 op_sel_hi:[1,0]
	v_pk_mul_f32 v[194:195], v[120:121], 0.5 op_sel_hi:[1,0]
	v_pk_mul_f32 v[222:223], v[110:111], 0.5 op_sel_hi:[1,0]
	v_pk_mul_f32 v[198:199], v[108:109], 0.5 op_sel_hi:[1,0]
	v_pk_mul_f32 v[192:193], v[102:103], 0.5 op_sel_hi:[1,0]
	v_pk_mul_f32 v[190:191], v[100:101], 0.5 op_sel_hi:[1,0]
	v_pk_mul_f32 v[184:185], v[118:119], 0.5 op_sel_hi:[1,0]
	v_pk_mul_f32 v[186:187], v[116:117], 0.5 op_sel_hi:[1,0]
	v_pk_mul_f32 v[178:179], v[114:115], 0.5 op_sel_hi:[1,0]
	v_pk_mul_f32 v[176:177], v[112:113], 0.5 op_sel_hi:[1,0]
	v_pk_mul_f32 v[182:183], v[94:95], 0.5 op_sel_hi:[1,0]
	v_pk_mul_f32 v[180:181], v[92:93], 0.5 op_sel_hi:[1,0]
	v_pk_mul_f32 v[170:171], v[86:87], 0.5 op_sel_hi:[1,0]
	v_pk_mul_f32 v[168:169], v[84:85], 0.5 op_sel_hi:[1,0]
	v_pk_mul_f32 v[164:165], v[106:107], 0.5 op_sel_hi:[1,0]
	v_pk_mul_f32 v[166:167], v[104:105], 0.5 op_sel_hi:[1,0]
	v_pk_mul_f32 v[158:159], v[98:99], 0.5 op_sel_hi:[1,0]
	v_pk_mul_f32 v[156:157], v[96:97], 0.5 op_sel_hi:[1,0]
	v_pk_mul_f32 v[162:163], v[78:79], 0.5 op_sel_hi:[1,0]
	v_pk_mul_f32 v[160:161], v[76:77], 0.5 op_sel_hi:[1,0]
	v_pk_mul_f32 v[154:155], v[74:75], 0.5 op_sel_hi:[1,0]
	v_pk_mul_f32 v[152:153], v[72:73], 0.5 op_sel_hi:[1,0]
	v_pk_mul_f32 v[148:149], v[90:91], 0.5 op_sel_hi:[1,0]
	v_pk_mul_f32 v[150:151], v[88:89], 0.5 op_sel_hi:[1,0]
	v_pk_mul_f32 v[142:143], v[82:83], 0.5 op_sel_hi:[1,0]
	v_pk_mul_f32 v[140:141], v[80:81], 0.5 op_sel_hi:[1,0]
	v_pk_mul_f32 v[146:147], v[70:71], 0.5 op_sel_hi:[1,0]
	v_pk_mul_f32 v[144:145], v[68:69], 0.5 op_sel_hi:[1,0]
	v_pk_mul_f32 v[138:139], v[66:67], 0.5 op_sel_hi:[1,0]
	v_pk_mul_f32 v[136:137], v[64:65], 0.5 op_sel_hi:[1,0]
	v_pk_mul_f32 v[126:127], v[62:63], 0.5 op_sel_hi:[1,0]
	v_pk_mul_f32 v[134:135], v[60:61], 0.5 op_sel_hi:[1,0]
	v_pk_mul_f32 v[118:119], v[58:59], 0.5 op_sel_hi:[1,0]
	v_pk_mul_f32 v[116:117], v[56:57], 0.5 op_sel_hi:[1,0]
	v_pk_mul_f32 v[122:123], v[46:47], 0.5 op_sel_hi:[1,0]
	v_pk_mul_f32 v[120:121], v[44:45], 0.5 op_sel_hi:[1,0]
	v_pk_mul_f32 v[114:115], v[38:39], 0.5 op_sel_hi:[1,0]
	v_pk_mul_f32 v[112:113], v[36:37], 0.5 op_sel_hi:[1,0]
	v_pk_mul_f32 v[110:111], v[54:55], 0.5 op_sel_hi:[1,0]
	v_pk_mul_f32 v[108:109], v[52:53], 0.5 op_sel_hi:[1,0]
	v_pk_mul_f32 v[102:103], v[50:51], 0.5 op_sel_hi:[1,0]
	v_pk_mul_f32 v[100:101], v[48:49], 0.5 op_sel_hi:[1,0]
	v_pk_mul_f32 v[106:107], v[30:31], 0.5 op_sel_hi:[1,0]
	v_pk_mul_f32 v[104:105], v[28:29], 0.5 op_sel_hi:[1,0]
	v_pk_mul_f32 v[98:99], v[22:23], 0.5 op_sel_hi:[1,0]
	v_pk_mul_f32 v[96:97], v[20:21], 0.5 op_sel_hi:[1,0]
	v_pk_mul_f32 v[94:95], v[42:43], 0.5 op_sel_hi:[1,0]
	v_pk_mul_f32 v[92:93], v[40:41], 0.5 op_sel_hi:[1,0]
	v_pk_mul_f32 v[86:87], v[34:35], 0.5 op_sel_hi:[1,0]
	v_pk_mul_f32 v[84:85], v[32:33], 0.5 op_sel_hi:[1,0]
	v_pk_mul_f32 v[90:91], v[14:15], 0.5 op_sel_hi:[1,0]
	v_pk_mul_f32 v[88:89], v[12:13], 0.5 op_sel_hi:[1,0]
	v_pk_mul_f32 v[82:83], v[10:11], 0.5 op_sel_hi:[1,0]
	v_pk_mul_f32 v[80:81], v[8:9], 0.5 op_sel_hi:[1,0]
	v_pk_mul_f32 v[78:79], v[26:27], 0.5 op_sel_hi:[1,0]
	v_pk_mul_f32 v[76:77], v[24:25], 0.5 op_sel_hi:[1,0]
	v_pk_mul_f32 v[70:71], v[18:19], 0.5 op_sel_hi:[1,0]
	v_pk_mul_f32 v[68:69], v[16:17], 0.5 op_sel_hi:[1,0]
	v_pk_mul_f32 v[74:75], v[6:7], 0.5 op_sel_hi:[1,0]
	v_pk_mul_f32 v[72:73], v[4:5], 0.5 op_sel_hi:[1,0]
	v_pk_mul_f32 v[66:67], v[2:3], 0.5 op_sel_hi:[1,0]
	v_pk_mul_f32 v[64:65], v[0:1], 0.5 op_sel_hi:[1,0]
